# P1 K-loop rewritten: 2 barriers per K-tile (64-MFMA epochs), asymmetric LDS-DMA staging 12/4
# baseline (speedup 1.0000x reference)
; #define PG8_STAGE(bufoff, gbase, voff) do { _Pragma("unroll") for (int _i = 0; _i < 2; ++_i) \
;         __builtin_amdgcn_global_load_lds((const unsigned*)((const char*)(gbase) + (voff)[_i]), (PG8_LAS unsigned*)(lds + (bufoff) + ldsw + _i * 8192), 16, 0, 0); } while (0)
; #define PG8_LDA(dst, b, h) do { _Pragma("unroll") for (int m = 0; m < 4; ++m) _Pragma("unroll") for (int k = 0; k < 2; ++k) dst[m][k] = *(const PG8_LAS bf16x8*)(lds + PG8_SA(b, h) + aoff + m * 2048 + k * 1024); } while (0)
; #define PG8_LDB(dst, b, h) do { _Pragma("unroll") for (int n = 0; n < 2; ++n) _Pragma("unroll") for (int k = 0; k < 2; ++k) dst[n][k] = *(const PG8_LAS bf16x8*)(lds + PG8_SB(b, h) + boff + n * 2048 + k * 1024); } while (0)
; #define PG8_MMA(ai, bj, At, Bt) do { __builtin_amdgcn_s_setprio(1); _Pragma("unroll") for (int m = 0; m < 4; ++m) _Pragma("unroll") for (int n = 0; n < 2; ++n) _Pragma("unroll") for (int k = 0; k < 2; ++k) \
;         acc[ai][bj][m][n] = __builtin_amdgcn_mfma_f32_16x16x32_bf16(Bt[n][k], At[m][k], acc[ai][bj][m][n], 0, 0, 0); __builtin_amdgcn_s_setprio(0); } while (0)
; #define PG8_BAR __builtin_amdgcn_s_barrier()
; template <class Epi, class Sched, bool ALIGN_EPI = false, bool SP2 = false>
; __device__ __forceinline__ void gemm_phase(PG8_LAS unsigned char* lds, const Gemm g, const Sched& S, const Epi& E) {
;     ...
;         for (int t = 0; t < nt; t += 2) {
;             if constexpr (Epi::MID) { if (t == nt / 2) E.mid(acc, cur, wr, fr, lds); }
;             const bool last = (t == nt - 2);
;             const char* a1 = cA + (size_t)(t + 1) * kstep;
;             const char* a2 = last ? nA : cA + (size_t)(t + 2) * kstep; const char* b2 = last ? nB : cB + (size_t)(t + 2) * kstep;
;             const char* a3 = a2 + kstep; const char* b3 = b2 + kstep;
;             if (last && has_next) S.a_ready(nxt);
;             if constexpr (SP2) {
;             PG8_LDB(B0, 0, 0); PG8_LDB(B1, 0, 1); PG8_SCHED; PG8_LDA(At, 0, 0); PG8_STAGE(PG8_SA(1, 1), a1 + hstep, voffA);
;             PG8_WAIT_V(8); PG8_WAIT_L(0); PG8_BAR; PG8_MMA(0, 0, At, B0); PG8_MMA(0, 1, At, B1); PG8_BAR; PG8_SCHED;
;     ...
;             PG8_LDA(At, 0, 1); PG8_STAGE(PG8_SB(0, 0), b2, voffB); PG8_STAGE(PG8_SB(0, 1), b2 + hstep, voffB); PG8_STAGE(PG8_SA(0, 0), a2, voffA);
;             PG8_WAIT_V(8); PG8_WAIT_L(0); PG8_BAR; PG8_MMA(1, 0, At, B0); PG8_MMA(1, 1, At, B1); PG8_BAR; PG8_SCHED;
.LBB0_133:
	s_cmp_lg_u64 s[70:71], 0
	s_cselect_b32 s33, 0, 0x10000
	s_add_u32 s0, s16, 0x80
	s_addc_u32 s1, s17, 0
	s_add_u32 s40, s2, 0x80
	s_addc_u32 s41, s3, 0
	s_mov_b32 s42, 0
	v_subrev_u32_e32 v244, s33, v142
	v_add_u32_e32 v245, 0x10000, v244
	v_add_u32_e32 v246, 0x20000, v244
	v_add_u32_e32 v247, 0x30000, v244
.Lk1_loop:
	s_cmp_lg_u64 s[70:71], 0
	s_cbranch_scc0 .Lk1_e_B
	s_cmp_eq_u32 s42, 0
	s_cbranch_scc1 .Lk1_e_Ar
	s_add_u32 s2, s40, 0x40000
	s_addc_u32 s3, s41, 0
	s_add_i32 m0, s21, 0x18000
	s_nop 0
	global_load_lds_dwordx4 v244, s[40:41]
	s_add_i32 m0, s21, 0x19000
	s_nop 0
	global_load_lds_dwordx4 v245, s[40:41]
	s_add_i32 m0, s21, 0x1a000
	s_nop 0
	global_load_lds_dwordx4 v246, s[40:41]
	s_add_i32 m0, s21, 0x1b000
	s_nop 0
	global_load_lds_dwordx4 v247, s[40:41]
	s_add_i32 m0, s21, 0x1c000
	s_nop 0
	global_load_lds_dwordx4 v244, s[2:3]
	s_add_i32 m0, s21, 0x1d000
	s_nop 0
	global_load_lds_dwordx4 v245, s[2:3]
	s_add_i32 m0, s21, 0x1e000
	s_nop 0
	global_load_lds_dwordx4 v246, s[2:3]
	s_add_i32 m0, s21, 0x1f000
	s_nop 0
	global_load_lds_dwordx4 v247, s[2:3]
	s_add_i32 m0, s21, 0x8000
	s_nop 0
	global_load_lds_dwordx4 v244, s[0:1]
	s_add_i32 m0, s21, 0x9000
	s_nop 0
	global_load_lds_dwordx4 v245, s[0:1]
	s_add_i32 m0, s21, 0xa000
	s_nop 0
	global_load_lds_dwordx4 v246, s[0:1]
	s_add_i32 m0, s21, 0xb000
	s_nop 0
	global_load_lds_dwordx4 v247, s[0:1]
.Lk1_e_Ar:
	ds_read_b128 v[82:85], v183 offset:0
	ds_read_b128 v[134:137], v183 offset:1024
	ds_read_b128 v[138:141], v183 offset:2048
	ds_read_b128 v[188:191], v183 offset:3072
	ds_read_b128 v[192:195], v184 offset:0
	ds_read_b128 v[196:199], v184 offset:1024
	ds_read_b128 v[200:203], v184 offset:2048
	ds_read_b128 v[204:207], v184 offset:3072
	ds_read_b128 v[208:211], v185 offset:0
	ds_read_b128 v[212:215], v185 offset:1024
	ds_read_b128 v[216:219], v185 offset:2048
	ds_read_b128 v[220:223], v185 offset:3072
	ds_read_b128 v[224:227], v185 offset:4096
	ds_read_b128 v[232:235], v185 offset:5120
	ds_read_b128 v[236:239], v185 offset:6144
	ds_read_b128 v[240:243], v185 offset:7168
	s_branch .Lk1_e_J
.Lk1_e_B:
	s_add_u32 s2, s0, 0x40000
	s_addc_u32 s3, s1, 0
	s_add_i32 m0, s21, 0xb000
	s_nop 0
	global_load_lds_dwordx4 v244, s[2:3]
	s_add_i32 m0, s21, 0xc000
	s_nop 0
	global_load_lds_dwordx4 v245, s[2:3]
	s_add_i32 m0, s21, 0xd000
	s_nop 0
	global_load_lds_dwordx4 v246, s[2:3]
	s_add_i32 m0, s21, 0xe000
	s_nop 0
	global_load_lds_dwordx4 v247, s[2:3]
	ds_read_b128 v[82:85], v183 offset:0
	ds_read_b128 v[134:137], v183 offset:1024
	ds_read_b128 v[138:141], v183 offset:2048
	ds_read_b128 v[188:191], v183 offset:3072
	ds_read_b128 v[192:195], v184 offset:0
	ds_read_b128 v[196:199], v184 offset:1024
	ds_read_b128 v[200:203], v184 offset:2048
	ds_read_b128 v[204:207], v184 offset:3072
	ds_read_b128 v[208:211], v185 offset:0
	ds_read_b128 v[212:215], v185 offset:1024
	ds_read_b128 v[216:219], v185 offset:2048
	ds_read_b128 v[220:223], v185 offset:3072
	ds_read_b128 v[224:227], v185 offset:4096
	ds_read_b128 v[232:235], v185 offset:5120
	ds_read_b128 v[236:239], v185 offset:6144
	ds_read_b128 v[240:243], v185 offset:7168
	s_waitcnt vmcnt(4)
.Lk1_e_J:
	s_waitcnt lgkmcnt(0)
	s_barrier
	s_setprio 1
	v_mfma_f32_16x16x32_bf16 v[122:125], v[82:85], v[208:211], v[122:125]
	v_mfma_f32_16x16x32_bf16 v[130:133], v[138:141], v[208:211], v[130:133]
	v_mfma_f32_16x16x32_bf16 v[126:129], v[192:195], v[208:211], v[126:129]
	v_mfma_f32_16x16x32_bf16 v[114:117], v[200:203], v[208:211], v[114:117]
	v_mfma_f32_16x16x32_bf16 v[122:125], v[134:137], v[212:215], v[122:125]
	v_mfma_f32_16x16x32_bf16 v[130:133], v[188:191], v[212:215], v[130:133]
	v_mfma_f32_16x16x32_bf16 v[126:129], v[196:199], v[212:215], v[126:129]
	v_mfma_f32_16x16x32_bf16 v[114:117], v[204:207], v[212:215], v[114:117]
	v_mfma_f32_16x16x32_bf16 v[106:109], v[82:85], v[216:219], v[106:109]
	ds_read_b128 v[208:211], v185 offset:16384
	ds_read_b128 v[212:215], v185 offset:17408
	v_mfma_f32_16x16x32_bf16 v[118:121], v[138:141], v[216:219], v[118:121]
	v_mfma_f32_16x16x32_bf16 v[110:113], v[192:195], v[216:219], v[110:113]
	v_mfma_f32_16x16x32_bf16 v[94:97], v[200:203], v[216:219], v[94:97]
	v_mfma_f32_16x16x32_bf16 v[106:109], v[134:137], v[220:223], v[106:109]
	v_mfma_f32_16x16x32_bf16 v[118:121], v[188:191], v[220:223], v[118:121]
	v_mfma_f32_16x16x32_bf16 v[110:113], v[196:199], v[220:223], v[110:113]
	v_mfma_f32_16x16x32_bf16 v[94:97], v[204:207], v[220:223], v[94:97]
	v_mfma_f32_16x16x32_bf16 v[90:93], v[82:85], v[224:227], v[90:93]
	ds_read_b128 v[216:219], v185 offset:18432
	ds_read_b128 v[220:223], v185 offset:19456
	v_mfma_f32_16x16x32_bf16 v[102:105], v[138:141], v[224:227], v[102:105]
	v_mfma_f32_16x16x32_bf16 v[98:101], v[192:195], v[224:227], v[98:101]
	v_mfma_f32_16x16x32_bf16 v[86:89], v[200:203], v[224:227], v[86:89]
	v_mfma_f32_16x16x32_bf16 v[90:93], v[134:137], v[232:235], v[90:93]
	v_mfma_f32_16x16x32_bf16 v[102:105], v[188:191], v[232:235], v[102:105]
	v_mfma_f32_16x16x32_bf16 v[98:101], v[196:199], v[232:235], v[98:101]
	v_mfma_f32_16x16x32_bf16 v[86:89], v[204:207], v[232:235], v[86:89]
	v_mfma_f32_16x16x32_bf16 v[68:71], v[82:85], v[236:239], v[68:71]
	ds_read_b128 v[224:227], v185 offset:20480
	ds_read_b128 v[232:235], v185 offset:21504
	v_mfma_f32_16x16x32_bf16 v[76:79], v[138:141], v[236:239], v[76:79]
	v_mfma_f32_16x16x32_bf16 v[72:75], v[192:195], v[236:239], v[72:75]
	v_mfma_f32_16x16x32_bf16 v[48:51], v[200:203], v[236:239], v[48:51]
	v_mfma_f32_16x16x32_bf16 v[68:71], v[134:137], v[240:243], v[68:71]
	v_mfma_f32_16x16x32_bf16 v[76:79], v[188:191], v[240:243], v[76:79]
	v_mfma_f32_16x16x32_bf16 v[72:75], v[196:199], v[240:243], v[72:75]
	v_mfma_f32_16x16x32_bf16 v[48:51], v[204:207], v[240:243], v[48:51]
	s_waitcnt lgkmcnt(4)
; #define PG8_STAGE(bufoff, gbase, voff) do { _Pragma("unroll") for (int _i = 0; _i < 2; ++_i) \
;         __builtin_amdgcn_global_load_lds((const unsigned*)((const char*)(gbase) + (voff)[_i]), (PG8_LAS unsigned*)(lds + (bufoff) + ldsw + _i * 8192), 16, 0, 0); } while (0)
; #define PG8_LDA(dst, b, h) do { _Pragma("unroll") for (int m = 0; m < 4; ++m) _Pragma("unroll") for (int k = 0; k < 2; ++k) dst[m][k] = *(const PG8_LAS bf16x8*)(lds + PG8_SA(b, h) + aoff + m * 2048 + k * 1024); } while (0)
; #define PG8_LDB(dst, b, h) do { _Pragma("unroll") for (int n = 0; n < 2; ++n) _Pragma("unroll") for (int k = 0; k < 2; ++k) dst[n][k] = *(const PG8_LAS bf16x8*)(lds + PG8_SB(b, h) + boff + n * 2048 + k * 1024); } while (0)
; #define PG8_MMA(ai, bj, At, Bt) do { __builtin_amdgcn_s_setprio(1); _Pragma("unroll") for (int m = 0; m < 4; ++m) _Pragma("unroll") for (int n = 0; n < 2; ++n) _Pragma("unroll") for (int k = 0; k < 2; ++k) \
;         acc[ai][bj][m][n] = __builtin_amdgcn_mfma_f32_16x16x32_bf16(Bt[n][k], At[m][k], acc[ai][bj][m][n], 0, 0, 0); __builtin_amdgcn_s_setprio(0); } while (0)
; #define PG8_WAIT_V(n) asm volatile("s_waitcnt vmcnt(" #n ")" ::: "memory")
; #define PG8_WAIT_L(n) asm volatile("s_waitcnt lgkmcnt(" #n ")" ::: "memory")
; #define PG8_BAR __builtin_amdgcn_s_barrier()
; #define PG8_SCHED __builtin_amdgcn_sched_barrier(0)
; template <class Epi, class Sched, bool ALIGN_EPI = false, bool SP2 = false>
; __device__ __forceinline__ void gemm_phase(PG8_LAS unsigned char* lds, const Gemm g, const Sched& S, const Epi& E) {
;     ...
;             PG8_WAIT_V(8); PG8_WAIT_L(0); PG8_BAR; PG8_MMA(1, 0, At, B0); PG8_MMA(1, 1, At, B1); PG8_BAR; PG8_SCHED;
;             PG8_LDB(B0, 1, 0); PG8_LDB(B1, 1, 1); PG8_SCHED; PG8_LDA(At, 1, 0); PG8_STAGE(PG8_SA(0, 1), a2 + hstep, voffA);
;             PG8_WAIT_V(8); PG8_WAIT_L(0); PG8_BAR; PG8_MMA(0, 0, At, B0); PG8_MMA(0, 1, At, B1); PG8_BAR; PG8_SCHED;
;             PG8_LDA(At, 1, 1); PG8_STAGE(PG8_SB(1, 0), b3, voffB); PG8_STAGE(PG8_SB(1, 1), b3 + hstep, voffB); PG8_STAGE(PG8_SA(1, 0), a3, voffA);
	v_mfma_f32_16x16x32_bf16 v[44:47], v[82:85], v[208:211], v[44:47]
	ds_read_b128 v[236:239], v185 offset:22528
	ds_read_b128 v[240:243], v185 offset:23552
	v_mfma_f32_16x16x32_bf16 v[60:63], v[138:141], v[208:211], v[60:63]
	v_mfma_f32_16x16x32_bf16 v[56:59], v[192:195], v[208:211], v[56:59]
	v_mfma_f32_16x16x32_bf16 v[32:35], v[200:203], v[208:211], v[32:35]
	v_mfma_f32_16x16x32_bf16 v[44:47], v[134:137], v[212:215], v[44:47]
	v_mfma_f32_16x16x32_bf16 v[60:63], v[188:191], v[212:215], v[60:63]
	v_mfma_f32_16x16x32_bf16 v[56:59], v[196:199], v[212:215], v[56:59]
	v_mfma_f32_16x16x32_bf16 v[32:35], v[204:207], v[212:215], v[32:35]
	s_waitcnt lgkmcnt(4)
	v_mfma_f32_16x16x32_bf16 v[28:31], v[82:85], v[216:219], v[28:31]
	v_mfma_f32_16x16x32_bf16 v[40:43], v[138:141], v[216:219], v[40:43]
	v_mfma_f32_16x16x32_bf16 v[36:39], v[192:195], v[216:219], v[36:39]
	v_mfma_f32_16x16x32_bf16 v[16:19], v[200:203], v[216:219], v[16:19]
	v_mfma_f32_16x16x32_bf16 v[28:31], v[134:137], v[220:223], v[28:31]
	v_mfma_f32_16x16x32_bf16 v[40:43], v[188:191], v[220:223], v[40:43]
	v_mfma_f32_16x16x32_bf16 v[36:39], v[196:199], v[220:223], v[36:39]
	v_mfma_f32_16x16x32_bf16 v[16:19], v[204:207], v[220:223], v[16:19]
	s_waitcnt lgkmcnt(2)
	v_mfma_f32_16x16x32_bf16 v[12:15], v[82:85], v[224:227], v[12:15]
	v_mfma_f32_16x16x32_bf16 v[24:27], v[138:141], v[224:227], v[24:27]
	v_mfma_f32_16x16x32_bf16 v[20:23], v[192:195], v[224:227], v[20:23]
	v_mfma_f32_16x16x32_bf16 v[8:11], v[200:203], v[224:227], v[8:11]
	v_mfma_f32_16x16x32_bf16 v[12:15], v[134:137], v[232:235], v[12:15]
	v_mfma_f32_16x16x32_bf16 v[24:27], v[188:191], v[232:235], v[24:27]
	v_mfma_f32_16x16x32_bf16 v[20:23], v[196:199], v[232:235], v[20:23]
	v_mfma_f32_16x16x32_bf16 v[8:11], v[204:207], v[232:235], v[8:11]
	s_waitcnt lgkmcnt(0)
	v_mfma_f32_16x16x32_bf16 v[4:7], v[82:85], v[236:239], v[4:7]
	v_mfma_f32_16x16x32_bf16 v[64:67], v[138:141], v[236:239], v[64:67]
	v_mfma_f32_16x16x32_bf16 v[52:55], v[192:195], v[236:239], v[52:55]
	v_mfma_f32_16x16x32_bf16 v[0:3], v[200:203], v[236:239], v[0:3]
	v_mfma_f32_16x16x32_bf16 v[4:7], v[134:137], v[240:243], v[4:7]
	v_mfma_f32_16x16x32_bf16 v[64:67], v[188:191], v[240:243], v[64:67]
	v_mfma_f32_16x16x32_bf16 v[52:55], v[196:199], v[240:243], v[52:55]
	v_mfma_f32_16x16x32_bf16 v[0:3], v[204:207], v[240:243], v[0:3]
	s_setprio 0
	s_waitcnt vmcnt(0)
	s_barrier
	s_add_u32 s0, s0, 0x80
	s_addc_u32 s1, s1, 0
	s_add_u32 s40, s40, 0x80
	s_addc_u32 s41, s41, 0
	s_cmp_eq_u32 s42, 7
	s_cselect_b32 s0, s37, s0
	s_cselect_b32 s1, s36, s1
	s_cselect_b32 s40, s39, s40
	s_cselect_b32 s41, s38, s41
	s_cmp_lg_u64 s[70:71], 0
	s_cbranch_scc0 .Lk1_o_B
	s_add_u32 s2, s40, 0x40000
	s_addc_u32 s3, s41, 0
	s_add_i32 m0, s21, 0x10000
	s_nop 0
	global_load_lds_dwordx4 v244, s[40:41]
	s_add_i32 m0, s21, 0x11000
	s_nop 0
	global_load_lds_dwordx4 v245, s[40:41]
	s_add_i32 m0, s21, 0x12000
	s_nop 0
	global_load_lds_dwordx4 v246, s[40:41]
	s_add_i32 m0, s21, 0x13000
	s_nop 0
	global_load_lds_dwordx4 v247, s[40:41]
	s_add_i32 m0, s21, 0x14000
	s_nop 0
	global_load_lds_dwordx4 v244, s[2:3]
	s_add_i32 m0, s21, 0x15000
	s_nop 0
	global_load_lds_dwordx4 v245, s[2:3]
	s_add_i32 m0, s21, 0x16000
	s_nop 0
	global_load_lds_dwordx4 v246, s[2:3]
	s_add_i32 m0, s21, 0x17000
	s_nop 0
	global_load_lds_dwordx4 v247, s[2:3]
	s_add_i32 m0, s21, 0x0
	s_nop 0
	global_load_lds_dwordx4 v244, s[0:1]
	s_add_i32 m0, s21, 0x1000
	s_nop 0
	global_load_lds_dwordx4 v245, s[0:1]
	s_add_i32 m0, s21, 0x2000
	s_nop 0
	global_load_lds_dwordx4 v246, s[0:1]
	s_add_i32 m0, s21, 0x3000
	s_nop 0
	global_load_lds_dwordx4 v247, s[0:1]
	ds_read_b128 v[82:85], v183 offset:32768
	ds_read_b128 v[134:137], v183 offset:33792
	ds_read_b128 v[138:141], v183 offset:34816
	ds_read_b128 v[188:191], v183 offset:35840
	ds_read_b128 v[192:195], v184 offset:32768
	ds_read_b128 v[196:199], v184 offset:33792
	ds_read_b128 v[200:203], v184 offset:34816
	ds_read_b128 v[204:207], v184 offset:35840
	ds_read_b128 v[208:211], v185 offset:32768
	ds_read_b128 v[212:215], v185 offset:33792
	ds_read_b128 v[216:219], v185 offset:34816
	ds_read_b128 v[220:223], v185 offset:35840
	ds_read_b128 v[224:227], v185 offset:36864
	ds_read_b128 v[232:235], v185 offset:37888
	ds_read_b128 v[236:239], v185 offset:38912
	ds_read_b128 v[240:243], v185 offset:39936
	s_branch .Lk1_o_J
.Lk1_o_B:
	s_add_u32 s2, s0, 0x40000
	s_addc_u32 s3, s1, 0
	s_add_i32 m0, s21, 0x3000
	s_nop 0
	global_load_lds_dwordx4 v244, s[2:3]
	s_add_i32 m0, s21, 0x4000
	s_nop 0
	global_load_lds_dwordx4 v245, s[2:3]
	s_add_i32 m0, s21, 0x5000
	s_nop 0
	global_load_lds_dwordx4 v246, s[2:3]
	s_add_i32 m0, s21, 0x6000
	s_nop 0
	global_load_lds_dwordx4 v247, s[2:3]
	ds_read_b128 v[82:85], v183 offset:32768
	ds_read_b128 v[134:137], v183 offset:33792
	ds_read_b128 v[138:141], v183 offset:34816
	ds_read_b128 v[188:191], v183 offset:35840
	ds_read_b128 v[192:195], v184 offset:32768
	ds_read_b128 v[196:199], v184 offset:33792
	ds_read_b128 v[200:203], v184 offset:34816
	ds_read_b128 v[204:207], v184 offset:35840
	ds_read_b128 v[208:211], v185 offset:32768
	ds_read_b128 v[212:215], v185 offset:33792
	ds_read_b128 v[216:219], v185 offset:34816
	ds_read_b128 v[220:223], v185 offset:35840
	ds_read_b128 v[224:227], v185 offset:36864
	ds_read_b128 v[232:235], v185 offset:37888
	ds_read_b128 v[236:239], v185 offset:38912
	ds_read_b128 v[240:243], v185 offset:39936
	s_waitcnt vmcnt(4)
; #define PG8_STAGE(bufoff, gbase, voff) do { _Pragma("unroll") for (int _i = 0; _i < 2; ++_i) \
;         __builtin_amdgcn_global_load_lds((const unsigned*)((const char*)(gbase) + (voff)[_i]), (PG8_LAS unsigned*)(lds + (bufoff) + ldsw + _i * 8192), 16, 0, 0); } while (0)
; #define PG8_LDA(dst, b, h) do { _Pragma("unroll") for (int m = 0; m < 4; ++m) _Pragma("unroll") for (int k = 0; k < 2; ++k) dst[m][k] = *(const PG8_LAS bf16x8*)(lds + PG8_SA(b, h) + aoff + m * 2048 + k * 1024); } while (0)
; #define PG8_MMA(ai, bj, At, Bt) do { __builtin_amdgcn_s_setprio(1); _Pragma("unroll") for (int m = 0; m < 4; ++m) _Pragma("unroll") for (int n = 0; n < 2; ++n) _Pragma("unroll") for (int k = 0; k < 2; ++k) \
;         acc[ai][bj][m][n] = __builtin_amdgcn_mfma_f32_16x16x32_bf16(Bt[n][k], At[m][k], acc[ai][bj][m][n], 0, 0, 0); __builtin_amdgcn_s_setprio(0); } while (0)
; #define PG8_WAIT_V(n) asm volatile("s_waitcnt vmcnt(" #n ")" ::: "memory")
; #define PG8_WAIT_L(n) asm volatile("s_waitcnt lgkmcnt(" #n ")" ::: "memory")
; #define PG8_BAR __builtin_amdgcn_s_barrier()
; #define PG8_SCHED __builtin_amdgcn_sched_barrier(0)
; template <class Epi, class Sched, bool ALIGN_EPI = false, bool SP2 = false>
; __device__ __forceinline__ void gemm_phase(PG8_LAS unsigned char* lds, const Gemm g, const Sched& S, const Epi& E) {
;     ...
;         for (int t = 0; t < nt; t += 2) {
;             if constexpr (Epi::MID) { if (t == nt / 2) E.mid(acc, cur, wr, fr, lds); }
;             const bool last = (t == nt - 2);
;             const char* a1 = cA + (size_t)(t + 1) * kstep;
;             const char* a2 = last ? nA : cA + (size_t)(t + 2) * kstep; const char* b2 = last ? nB : cB + (size_t)(t + 2) * kstep;
;     ...
;             PG8_LDA(At, 1, 1); PG8_STAGE(PG8_SB(1, 0), b3, voffB); PG8_STAGE(PG8_SB(1, 1), b3 + hstep, voffB); PG8_STAGE(PG8_SA(1, 0), a3, voffA);
;             PG8_WAIT_V(8); PG8_WAIT_L(0); PG8_BAR; PG8_MMA(1, 0, At, B0); PG8_MMA(1, 1, At, B1); PG8_BAR; PG8_SCHED;
.Lk1_o_J:
	s_waitcnt lgkmcnt(0)
	s_barrier
	s_setprio 1
	v_mfma_f32_16x16x32_bf16 v[122:125], v[82:85], v[208:211], v[122:125]
	v_mfma_f32_16x16x32_bf16 v[130:133], v[138:141], v[208:211], v[130:133]
	v_mfma_f32_16x16x32_bf16 v[126:129], v[192:195], v[208:211], v[126:129]
	v_mfma_f32_16x16x32_bf16 v[114:117], v[200:203], v[208:211], v[114:117]
	v_mfma_f32_16x16x32_bf16 v[122:125], v[134:137], v[212:215], v[122:125]
	v_mfma_f32_16x16x32_bf16 v[130:133], v[188:191], v[212:215], v[130:133]
	v_mfma_f32_16x16x32_bf16 v[126:129], v[196:199], v[212:215], v[126:129]
	v_mfma_f32_16x16x32_bf16 v[114:117], v[204:207], v[212:215], v[114:117]
	v_mfma_f32_16x16x32_bf16 v[106:109], v[82:85], v[216:219], v[106:109]
	ds_read_b128 v[208:211], v185 offset:49152
	ds_read_b128 v[212:215], v185 offset:50176
	v_mfma_f32_16x16x32_bf16 v[118:121], v[138:141], v[216:219], v[118:121]
	v_mfma_f32_16x16x32_bf16 v[110:113], v[192:195], v[216:219], v[110:113]
	v_mfma_f32_16x16x32_bf16 v[94:97], v[200:203], v[216:219], v[94:97]
	v_mfma_f32_16x16x32_bf16 v[106:109], v[134:137], v[220:223], v[106:109]
	v_mfma_f32_16x16x32_bf16 v[118:121], v[188:191], v[220:223], v[118:121]
	v_mfma_f32_16x16x32_bf16 v[110:113], v[196:199], v[220:223], v[110:113]
	v_mfma_f32_16x16x32_bf16 v[94:97], v[204:207], v[220:223], v[94:97]
	v_mfma_f32_16x16x32_bf16 v[90:93], v[82:85], v[224:227], v[90:93]
	ds_read_b128 v[216:219], v185 offset:51200
	ds_read_b128 v[220:223], v185 offset:52224
	v_mfma_f32_16x16x32_bf16 v[102:105], v[138:141], v[224:227], v[102:105]
	v_mfma_f32_16x16x32_bf16 v[98:101], v[192:195], v[224:227], v[98:101]
	v_mfma_f32_16x16x32_bf16 v[86:89], v[200:203], v[224:227], v[86:89]
	v_mfma_f32_16x16x32_bf16 v[90:93], v[134:137], v[232:235], v[90:93]
	v_mfma_f32_16x16x32_bf16 v[102:105], v[188:191], v[232:235], v[102:105]
	v_mfma_f32_16x16x32_bf16 v[98:101], v[196:199], v[232:235], v[98:101]
	v_mfma_f32_16x16x32_bf16 v[86:89], v[204:207], v[232:235], v[86:89]
	v_mfma_f32_16x16x32_bf16 v[68:71], v[82:85], v[236:239], v[68:71]
	ds_read_b128 v[224:227], v185 offset:53248
	ds_read_b128 v[232:235], v185 offset:54272
	v_mfma_f32_16x16x32_bf16 v[76:79], v[138:141], v[236:239], v[76:79]
	v_mfma_f32_16x16x32_bf16 v[72:75], v[192:195], v[236:239], v[72:75]
	v_mfma_f32_16x16x32_bf16 v[48:51], v[200:203], v[236:239], v[48:51]
	v_mfma_f32_16x16x32_bf16 v[68:71], v[134:137], v[240:243], v[68:71]
	v_mfma_f32_16x16x32_bf16 v[76:79], v[188:191], v[240:243], v[76:79]
	v_mfma_f32_16x16x32_bf16 v[72:75], v[196:199], v[240:243], v[72:75]
	v_mfma_f32_16x16x32_bf16 v[48:51], v[204:207], v[240:243], v[48:51]
	s_waitcnt lgkmcnt(4)
	v_mfma_f32_16x16x32_bf16 v[44:47], v[82:85], v[208:211], v[44:47]
	ds_read_b128 v[236:239], v185 offset:55296
	ds_read_b128 v[240:243], v185 offset:56320
	v_mfma_f32_16x16x32_bf16 v[60:63], v[138:141], v[208:211], v[60:63]
	v_mfma_f32_16x16x32_bf16 v[56:59], v[192:195], v[208:211], v[56:59]
	v_mfma_f32_16x16x32_bf16 v[32:35], v[200:203], v[208:211], v[32:35]
	v_mfma_f32_16x16x32_bf16 v[44:47], v[134:137], v[212:215], v[44:47]
	v_mfma_f32_16x16x32_bf16 v[60:63], v[188:191], v[212:215], v[60:63]
	v_mfma_f32_16x16x32_bf16 v[56:59], v[196:199], v[212:215], v[56:59]
	v_mfma_f32_16x16x32_bf16 v[32:35], v[204:207], v[212:215], v[32:35]
	s_waitcnt lgkmcnt(4)
	v_mfma_f32_16x16x32_bf16 v[28:31], v[82:85], v[216:219], v[28:31]
	v_mfma_f32_16x16x32_bf16 v[40:43], v[138:141], v[216:219], v[40:43]
	v_mfma_f32_16x16x32_bf16 v[36:39], v[192:195], v[216:219], v[36:39]
	v_mfma_f32_16x16x32_bf16 v[16:19], v[200:203], v[216:219], v[16:19]
	v_mfma_f32_16x16x32_bf16 v[28:31], v[134:137], v[220:223], v[28:31]
	v_mfma_f32_16x16x32_bf16 v[40:43], v[188:191], v[220:223], v[40:43]
	v_mfma_f32_16x16x32_bf16 v[36:39], v[196:199], v[220:223], v[36:39]
	v_mfma_f32_16x16x32_bf16 v[16:19], v[204:207], v[220:223], v[16:19]
	s_waitcnt lgkmcnt(2)
	v_mfma_f32_16x16x32_bf16 v[12:15], v[82:85], v[224:227], v[12:15]
	v_mfma_f32_16x16x32_bf16 v[24:27], v[138:141], v[224:227], v[24:27]
	v_mfma_f32_16x16x32_bf16 v[20:23], v[192:195], v[224:227], v[20:23]
	v_mfma_f32_16x16x32_bf16 v[8:11], v[200:203], v[224:227], v[8:11]
	v_mfma_f32_16x16x32_bf16 v[12:15], v[134:137], v[232:235], v[12:15]
	v_mfma_f32_16x16x32_bf16 v[24:27], v[188:191], v[232:235], v[24:27]
	v_mfma_f32_16x16x32_bf16 v[20:23], v[196:199], v[232:235], v[20:23]
	v_mfma_f32_16x16x32_bf16 v[8:11], v[204:207], v[232:235], v[8:11]
	s_waitcnt lgkmcnt(0)
	v_mfma_f32_16x16x32_bf16 v[4:7], v[82:85], v[236:239], v[4:7]
	v_mfma_f32_16x16x32_bf16 v[64:67], v[138:141], v[236:239], v[64:67]
	v_mfma_f32_16x16x32_bf16 v[52:55], v[192:195], v[236:239], v[52:55]
	v_mfma_f32_16x16x32_bf16 v[0:3], v[200:203], v[236:239], v[0:3]
	v_mfma_f32_16x16x32_bf16 v[4:7], v[134:137], v[240:243], v[4:7]
	v_mfma_f32_16x16x32_bf16 v[64:67], v[188:191], v[240:243], v[64:67]
	v_mfma_f32_16x16x32_bf16 v[52:55], v[196:199], v[240:243], v[52:55]
	v_mfma_f32_16x16x32_bf16 v[0:3], v[204:207], v[240:243], v[0:3]
	s_setprio 0
	s_waitcnt vmcnt(0)
	s_barrier
	s_add_u32 s0, s0, 0x80
	s_addc_u32 s1, s1, 0
	s_add_u32 s40, s40, 0x80
	s_addc_u32 s41, s41, 0
	s_add_i32 s42, s42, 1
	s_cmp_lt_u32 s42, 8
	s_cbranch_scc1 .Lk1_loop
	s_and_b64 vcc, exec, s[70:71]
	s_cbranch_vccnz .LBB0_137
	s_cmp_lt_i32 s60, 9
	s_mov_b64 s[0:1], -1
	s_cbranch_scc1 .LBB0_138

; #define PG8_BAR __builtin_amdgcn_s_barrier()
; template <class Epi, class Sched, bool ALIGN_EPI = false, bool SP2 = false>
; __device__ __forceinline__ void gemm_phase(PG8_LAS unsigned char* lds, const Gemm g, const Sched& S, const Epi& E) {
;     ...
;         if constexpr (ALIGN_EPI) { if (wr == 0) PG8_BAR; }
;         if constexpr (!Epi::AFTER_DRAIN) { E(acc, cur, wr, wc, fr, fq, lds); S.done(cur); }
.LBB0_137:
	s_add_u32 s2, s40, 0x40000
	s_addc_u32 s3, s41, 0
	s_add_i32 m0, s21, 0x18000
	s_nop 0
	global_load_lds_dwordx4 v244, s[40:41]
	s_add_i32 m0, s21, 0x19000
	s_nop 0
	global_load_lds_dwordx4 v245, s[40:41]
	s_add_i32 m0, s21, 0x1a000
	s_nop 0
	global_load_lds_dwordx4 v246, s[40:41]
	s_add_i32 m0, s21, 0x1b000
	s_nop 0
	global_load_lds_dwordx4 v247, s[40:41]
	s_add_i32 m0, s21, 0x1c000
	s_nop 0
	global_load_lds_dwordx4 v244, s[2:3]
	s_add_i32 m0, s21, 0x1d000
	s_nop 0
	global_load_lds_dwordx4 v245, s[2:3]
	s_add_i32 m0, s21, 0x1e000
	s_nop 0
	global_load_lds_dwordx4 v246, s[2:3]
	s_add_i32 m0, s21, 0x1f000
	s_nop 0
	global_load_lds_dwordx4 v247, s[2:3]
	s_add_i32 m0, s21, 0x8000
	s_nop 0
	global_load_lds_dwordx4 v244, s[0:1]
	s_add_i32 m0, s21, 0x9000
	s_nop 0
	global_load_lds_dwordx4 v245, s[0:1]
	s_add_i32 m0, s21, 0xa000
	s_nop 0
	global_load_lds_dwordx4 v246, s[0:1]
	s_add_i32 m0, s21, 0xb000
	s_nop 0
	global_load_lds_dwordx4 v247, s[0:1]
	s_barrier
	s_cmp_lt_i32 s60, 9
	s_mov_b64 s[0:1], -1
	s_cbranch_scc0 .LBB0_136
